# NA: hoist all PV tr-reads of a tile into extra VGPRs (v148-159) ahead of the MFMAs, de-serialise tile-B bias LDS reads into one batch
# speedup vs baseline: 1.0056x; 1.0044x over previous
.LBB0_610:
	v_add_f32_e32 v222, 0, v234
	v_add_f32_e32 v222, v235, v222
	v_add_f32_e32 v222, v236, v222
	v_add_f32_e32 v222, v237, v222
	v_add_f32_e32 v222, v238, v222
	v_add_f32_e32 v222, v239, v222
	v_add_f32_e32 v222, v240, v222
	v_add_f32_e32 v222, v241, v222
	v_add_f32_e32 v222, v242, v222
	v_add_f32_e32 v222, v243, v222
	v_add_f32_e32 v222, v244, v222
	v_add_f32_e32 v222, v245, v222
	v_add_f32_e32 v222, v246, v222
	v_add_f32_e32 v222, v247, v222
	v_add_f32_e32 v222, v248, v222
	v_add_f32_e32 v234, v249, v222
	v_fmac_f32_e32 v234, v232, v140
	v_max_f32_e32 v140, v33, v33
	v_max_f32_e32 v222, v32, v32
	v_max_f32_e32 v140, v222, v140
	v_max3_f32 v140, v140, v34, v35
	v_max3_f32 v140, v140, v36, v37
	v_max3_f32 v140, v140, v38, v39
	v_max3_f32 v140, v140, v40, v41
	v_max3_f32 v140, v140, v42, v43
	v_max3_f32 v140, v140, v44, v45
	v_max3_f32 v140, v140, v46, v47
	ds_bpermute_b32 v222, v169, v140
	s_waitcnt lgkmcnt(0)
	s_addk_i32 s83, 0x80
	s_add_i32 s93, s93, 2
	s_add_i32 s87, s87, 64
	s_waitcnt lgkmcnt(0)
	ds_read_b64_tr_b16 v[148:149], v229 offset:64
	ds_read_b64_tr_b16 v[150:151], v229 offset:1216
	ds_read_b64_tr_b16 v[152:153], v229 offset:2304
	ds_read_b64_tr_b16 v[154:155], v229 offset:3456
	ds_read_b64_tr_b16 v[156:157], v229 offset:2368
	ds_read_b64_tr_b16 v[158:159], v229 offset:3520
	v_max3_f32 v140, v233, v140, v222
	v_sub_f32_e32 v32, v32, v140
	v_exp_f32_e32 v223, v32
	v_sub_f32_e32 v32, v33, v140
	v_exp_f32_e32 v33, v32
	v_sub_f32_e32 v32, v34, v140
	v_exp_f32_e32 v224, v32
	v_sub_f32_e32 v32, v35, v140
	v_exp_f32_e32 v35, v32
	v_sub_f32_e32 v32, v36, v140
	v_exp_f32_e32 v36, v32
	v_sub_f32_e32 v32, v37, v140
	v_add_f32_e32 v34, 0, v223
	v_exp_f32_e32 v37, v32
	v_sub_f32_e32 v32, v38, v140
	v_add_f32_e32 v34, v33, v34
	v_exp_f32_e32 v38, v32
	v_sub_f32_e32 v32, v39, v140
	v_add_f32_e32 v34, v224, v34
	v_exp_f32_e32 v39, v32
	v_sub_f32_e32 v32, v40, v140
	v_add_f32_e32 v34, v35, v34
	v_exp_f32_e32 v225, v32
	v_sub_f32_e32 v32, v41, v140
	v_add_f32_e32 v34, v36, v34
	v_exp_f32_e32 v226, v32
	v_sub_f32_e32 v32, v42, v140
	v_add_f32_e32 v34, v37, v34
	v_exp_f32_e32 v42, v32
	v_sub_f32_e32 v32, v43, v140
	v_add_f32_e32 v34, v38, v34
	v_exp_f32_e32 v43, v32
	v_sub_f32_e32 v32, v44, v140
	v_add_f32_e32 v34, v39, v34
	v_exp_f32_e32 v44, v32
	v_sub_f32_e32 v32, v45, v140
	v_add_f32_e32 v34, v225, v34
	v_exp_f32_e32 v45, v32
	v_sub_f32_e32 v32, v46, v140
	v_add_f32_e32 v34, v226, v34
	v_sub_f32_e32 v222, v233, v140
	v_exp_f32_e32 v46, v32
	v_sub_f32_e32 v32, v47, v140
	v_add_f32_e32 v34, v42, v34
	v_exp_f32_e32 v47, v32
	v_exp_f32_e32 v32, v222
	v_add_f32_e32 v34, v43, v34
	v_add_f32_e32 v34, v44, v34
	v_add_f32_e32 v34, v45, v34
	v_add_f32_e32 v34, v46, v34
	v_pk_mul_f32 v[14:15], v[14:15], v[32:33] op_sel_hi:[1,0]
	v_pk_mul_f32 v[12:13], v[12:13], v[32:33] op_sel_hi:[1,0]
	v_pk_mul_f32 v[10:11], v[10:11], v[32:33] op_sel_hi:[1,0]
	v_pk_mul_f32 v[8:9], v[8:9], v[32:33] op_sel_hi:[1,0]
	v_pk_mul_f32 v[6:7], v[6:7], v[32:33] op_sel_hi:[1,0]
	v_pk_mul_f32 v[4:5], v[4:5], v[32:33] op_sel_hi:[1,0]
	v_pk_mul_f32 v[2:3], v[2:3], v[32:33] op_sel_hi:[1,0]
	v_pk_mul_f32 v[0:1], v[0:1], v[32:33] op_sel_hi:[1,0]
	v_add_f32_e32 v232, v47, v34
	v_cvt_pk_bf16_f32 v34, v223, v33
	v_cvt_pk_bf16_f32 v35, v224, v35
	v_cvt_pk_bf16_f32 v36, v36, v37
	v_cvt_pk_bf16_f32 v37, v38, v39
	ds_read_b64_tr_b16 v[38:39], v229
	ds_read_b64_tr_b16 v[40:41], v229 offset:1152
	s_waitcnt lgkmcnt(2)
	v_pk_mul_f32 v[30:31], v[30:31], v[32:33] op_sel_hi:[1,0]
	s_waitcnt lgkmcnt(0)
	v_pk_mul_f32 v[28:29], v[28:29], v[32:33] op_sel_hi:[1,0]
	v_pk_mul_f32 v[26:27], v[26:27], v[32:33] op_sel_hi:[1,0]
	v_pk_mul_f32 v[24:25], v[24:25], v[32:33] op_sel_hi:[1,0]
	v_pk_mul_f32 v[22:23], v[22:23], v[32:33] op_sel_hi:[1,0]
	v_pk_mul_f32 v[20:21], v[20:21], v[32:33] op_sel_hi:[1,0]
	v_pk_mul_f32 v[18:19], v[18:19], v[32:33] op_sel_hi:[1,0]
	v_pk_mul_f32 v[16:17], v[16:17], v[32:33] op_sel_hi:[1,0]
	v_fmac_f32_e32 v232, v234, v32
	s_cmp_lt_u32 s33, s84
	v_mfma_f32_32x32x16_bf16 v[16:31], v[38:41], v[34:37], v[16:31]
	s_waitcnt lgkmcnt(2)
	s_waitcnt lgkmcnt(0)
	s_nop 1
	v_mfma_f32_32x32x16_bf16 v[0:15], v[148:151], v[34:37], v[0:15]
	v_cvt_pk_bf16_f32 v35, v42, v43
	v_cvt_pk_bf16_f32 v36, v44, v45
	s_waitcnt lgkmcnt(2)
	v_cvt_pk_bf16_f32 v34, v225, v226
	s_waitcnt lgkmcnt(0)
	v_cvt_pk_bf16_f32 v37, v46, v47
	s_nop 1
	v_mfma_f32_32x32x16_bf16 v[16:31], v[152:155], v[34:37], v[16:31]
	s_waitcnt lgkmcnt(2)
	s_waitcnt lgkmcnt(0)
	s_nop 1
	v_mfma_f32_32x32x16_bf16 v[0:15], v[156:159], v[34:37], v[0:15]
	s_cbranch_scc0 .LBB0_595

.LBB0_619:
	s_nop 3
	v_max_f32_e32 v222, v33, v33
	v_max_f32_e32 v223, v32, v32
	v_max_f32_e32 v222, v223, v222
	v_max3_f32 v222, v222, v34, v35
	v_max3_f32 v222, v222, v36, v37
	v_max3_f32 v222, v222, v38, v39
	v_max3_f32 v222, v222, v40, v41
	v_max3_f32 v222, v222, v42, v43
	v_max3_f32 v222, v222, v44, v45
	v_max3_f32 v222, v222, v46, v47
	ds_bpermute_b32 v223, v169, v222
	s_waitcnt lgkmcnt(0)
	s_add_i32 s0, s93, 17
	s_cmp_ge_u32 s0, s84
	s_waitcnt lgkmcnt(0)
	v_max3_f32 v233, v140, v222, v223
	v_sub_f32_e32 v32, v32, v233
	v_exp_f32_e32 v234, v32
	v_sub_f32_e32 v32, v33, v233
	v_exp_f32_e32 v235, v32
	v_sub_f32_e32 v32, v34, v233
	v_exp_f32_e32 v236, v32
	v_sub_f32_e32 v32, v35, v233
	v_exp_f32_e32 v237, v32
	v_sub_f32_e32 v32, v36, v233
	v_exp_f32_e32 v238, v32
	v_sub_f32_e32 v32, v37, v233
	v_exp_f32_e32 v239, v32
	v_sub_f32_e32 v32, v38, v233
	v_exp_f32_e32 v240, v32
	v_sub_f32_e32 v32, v39, v233
	v_exp_f32_e32 v241, v32
	v_sub_f32_e32 v32, v40, v233
	v_exp_f32_e32 v242, v32
	v_sub_f32_e32 v32, v41, v233
	v_exp_f32_e32 v243, v32
	v_sub_f32_e32 v32, v42, v233
	v_exp_f32_e32 v244, v32
	v_sub_f32_e32 v32, v43, v233
	ds_read_b64_tr_b16 v[36:37], v229
	ds_read_b64_tr_b16 v[38:39], v229 offset:1152
	ds_read_b64_tr_b16 v[148:149], v229 offset:64
	ds_read_b64_tr_b16 v[150:151], v229 offset:1216
	ds_read_b64_tr_b16 v[152:153], v229 offset:2304
	ds_read_b64_tr_b16 v[154:155], v229 offset:3456
	ds_read_b64_tr_b16 v[156:157], v229 offset:2368
	ds_read_b64_tr_b16 v[158:159], v229 offset:3520
	v_sub_f32_e32 v140, v140, v233
	v_exp_f32_e32 v245, v32
	v_sub_f32_e32 v32, v44, v233
	v_exp_f32_e32 v140, v140
	v_exp_f32_e32 v246, v32
	v_sub_f32_e32 v32, v45, v233
	v_exp_f32_e32 v247, v32
	v_sub_f32_e32 v32, v46, v233
	v_exp_f32_e32 v248, v32
	v_sub_f32_e32 v32, v47, v233
	v_exp_f32_e32 v249, v32
	v_cvt_pk_bf16_f32 v32, v234, v235
	v_cvt_pk_bf16_f32 v33, v236, v237
	v_cvt_pk_bf16_f32 v34, v238, v239
	v_cvt_pk_bf16_f32 v35, v240, v241
	v_pk_mul_f32 v[30:31], v[30:31], v[140:141] op_sel_hi:[1,0]
	v_pk_mul_f32 v[28:29], v[28:29], v[140:141] op_sel_hi:[1,0]
	v_pk_mul_f32 v[26:27], v[26:27], v[140:141] op_sel_hi:[1,0]
	v_pk_mul_f32 v[24:25], v[24:25], v[140:141] op_sel_hi:[1,0]
	v_pk_mul_f32 v[22:23], v[22:23], v[140:141] op_sel_hi:[1,0]
	v_pk_mul_f32 v[20:21], v[20:21], v[140:141] op_sel_hi:[1,0]
	v_pk_mul_f32 v[18:19], v[18:19], v[140:141] op_sel_hi:[1,0]
	v_pk_mul_f32 v[16:17], v[16:17], v[140:141] op_sel_hi:[1,0]
	v_pk_mul_f32 v[14:15], v[14:15], v[140:141] op_sel_hi:[1,0]
	v_pk_mul_f32 v[12:13], v[12:13], v[140:141] op_sel_hi:[1,0]
	s_waitcnt lgkmcnt(6)
	v_mfma_f32_32x32x16_bf16 v[16:31], v[36:39], v[32:35], v[16:31]
	v_pk_mul_f32 v[10:11], v[10:11], v[140:141] op_sel_hi:[1,0]
	v_pk_mul_f32 v[8:9], v[8:9], v[140:141] op_sel_hi:[1,0]
	v_pk_mul_f32 v[6:7], v[6:7], v[140:141] op_sel_hi:[1,0]
	v_pk_mul_f32 v[4:5], v[4:5], v[140:141] op_sel_hi:[1,0]
	v_pk_mul_f32 v[2:3], v[2:3], v[140:141] op_sel_hi:[1,0]
	v_pk_mul_f32 v[0:1], v[0:1], v[140:141] op_sel_hi:[1,0]
	s_nop 1
	s_waitcnt lgkmcnt(4)
	v_mfma_f32_32x32x16_bf16 v[0:15], v[148:151], v[32:35], v[0:15]
	v_cvt_pk_bf16_f32 v32, v242, v243
	v_cvt_pk_bf16_f32 v33, v244, v245
	v_cvt_pk_bf16_f32 v34, v246, v247
	v_cvt_pk_bf16_f32 v35, v248, v249
	s_nop 1
	s_waitcnt lgkmcnt(2)
	v_mfma_f32_32x32x16_bf16 v[16:31], v[152:155], v[32:35], v[16:31]
	s_waitcnt lgkmcnt(2)
	s_waitcnt lgkmcnt(0)
	s_waitcnt vmcnt(3)
	ds_write_b128 v184, v[96:99] offset:46080
	ds_write_b128 v184, v[100:103] offset:47232
	ds_write_b128 v184, v[104:107] offset:48384
	ds_write_b128 v184, v[108:111] offset:49536
	s_waitcnt lgkmcnt(0)
	ds_read_b128 v[96:99], v185 offset:46080
	ds_read_b128 v[100:103], v185 offset:46112
	ds_read_b128 v[104:107], v185 offset:46144
	ds_read_b128 v[108:111], v185 offset:46176
	ds_write_b128 v184, v[112:115]
	s_waitcnt vmcnt(0)
	ds_write_b128 v184, v[124:127] offset:1152
	ds_write_b128 v184, v[120:123] offset:2304
	ds_write_b128 v184, v[116:119] offset:3456
	v_mfma_f32_32x32x16_bf16 v[0:15], v[156:159], v[32:35], v[0:15]
	s_waitcnt lgkmcnt(4)
	v_mfma_f32_32x32x16_bf16 v[32:47], v[96:99], v[48:51], 0
	v_mfma_f32_32x32x16_bf16 v[32:47], v[100:103], v[52:55], v[32:47]
	v_mfma_f32_32x32x16_bf16 v[32:47], v[104:107], v[56:59], v[32:47]
	v_mfma_f32_32x32x16_bf16 v[32:47], v[108:111], v[60:63], v[32:47]
	s_cbranch_scc1 .LBB0_623
	s_cmp_lt_u32 s81, 13
	s_cselect_b64 vcc, -1, 0
	s_and_b64 vcc, s[76:77], vcc
	s_and_b64 vcc, exec, vcc
	s_mov_b32 s1, s87
	s_cbranch_vccnz .LBB0_622
	s_add_i32 s1, s93, 1
	s_and_b64 vcc, s[76:77], exec
	s_cselect_b32 s0, s1, s0
	s_lshl_b32 s0, s0, 5
	s_add_i32 s1, s0, s86

.LBB0_623:
	s_and_b64 vcc, exec, s[68:69]
	s_cbranch_vccnz .LBB0_610
	v_add_u32_e32 v222, s83, v206
	v_add_u32_e32 v223, s83, v205
	v_add_u32_e32 v224, s83, v204
	v_add_u32_e32 v225, s83, v203
	v_add_u32_e32 v148, s83, v202
	v_add_u32_e32 v149, s83, v201
	v_add_u32_e32 v150, s83, v200
	v_add_u32_e32 v151, s83, v199
	v_add_u32_e32 v152, s83, v198
	v_add_u32_e32 v153, s83, v193
	v_add_u32_e32 v154, s83, v192
	v_add_u32_e32 v155, s83, v191
	s_waitcnt lgkmcnt(3)
	ds_read_b32 v222, v222 offset:4608
	ds_read_b32 v223, v223 offset:4608
	ds_read_b32 v224, v224 offset:4608
	ds_read_b32 v225, v225 offset:4608
	ds_read_b32 v148, v148 offset:4608
	ds_read_b32 v149, v149 offset:4608
	ds_read_b32 v150, v150 offset:4608
	ds_read_b32 v151, v151 offset:4608
	ds_read_b32 v152, v152 offset:4608
	ds_read_b32 v153, v153 offset:4608
	ds_read_b32 v154, v154 offset:4608
	ds_read_b32 v155, v155 offset:4608
	v_add_u32_e32 v156, s83, v190
	v_add_u32_e32 v157, s83, v189
	v_add_u32_e32 v158, s83, v188
	v_add_u32_e32 v159, s83, v161
	s_waitcnt lgkmcnt(8)
	ds_read_b32 v156, v156 offset:4608
	ds_read_b32 v157, v157 offset:4608
	ds_read_b32 v158, v158 offset:4608
	ds_read_b32 v159, v159 offset:4608
	v_pk_add_f32 v[32:33], v[32:33], v[222:223]
	v_pk_add_f32 v[34:35], v[34:35], v[224:225]
	s_waitcnt lgkmcnt(8)
	v_pk_add_f32 v[36:37], v[36:37], v[148:149]
	v_pk_add_f32 v[38:39], v[38:39], v[150:151]
	s_waitcnt lgkmcnt(4)
	v_pk_add_f32 v[40:41], v[40:41], v[152:153]
	v_pk_add_f32 v[42:43], v[42:43], v[154:155]
	s_waitcnt lgkmcnt(0)
	v_pk_add_f32 v[44:45], v[44:45], v[156:157]
	v_pk_add_f32 v[46:47], v[46:47], v[158:159]
	v_cndmask_b32_e64 v32, v230, v32, s[36:37]
	v_cndmask_b32_e64 v33, v230, v33, s[38:39]
	v_cndmask_b32_e64 v34, v230, v34, s[40:41]
	v_cndmask_b32_e64 v35, v230, v35, s[42:43]
	v_cndmask_b32_e64 v36, v230, v36, s[54:55]
	v_cndmask_b32_e64 v37, v230, v37, s[56:57]
	v_cndmask_b32_e64 v38, v230, v38, s[58:59]
	v_cndmask_b32_e64 v39, v230, v39, s[60:61]
	v_cndmask_b32_e64 v40, v230, v40, s[46:47]
	v_cndmask_b32_e64 v41, v230, v41, s[44:45]
	v_cndmask_b32_e64 v42, v230, v42, s[50:51]
	v_cndmask_b32_e64 v43, v230, v43, s[48:49]
	v_cndmask_b32_e64 v44, v230, v44, s[62:63]
	v_cndmask_b32_e64 v45, v230, v45, s[52:53]
	v_cndmask_b32_e64 v46, v230, v46, s[66:67]
	v_cndmask_b32_e64 v47, v230, v47, s[64:65]
	s_branch .LBB0_610
